# attn loop: V fragment reads issued under the last QK MFMAs and PV MFMAs start immediately after QK (row-max VALU delayed two MFMAs instead of nop padding); 4-tuple ring
# speedup vs baseline: 1.0089x; 1.0052x over previous
; __device__ __forceinline__ void finishSM(f32x16& p0, f32x16& p1, float alpha, float& l_reg, bf16x8& pa0, bf16x8& pa1, bf16x8& pa2, bf16x8& pa3) {
; #pragma unroll
;   for (int r = 0; r < 16; ++r) p1[r] = __builtin_amdgcn_exp2f(p1[r]);
;   float ps = 0;
; #pragma unroll
;   for (int r = 0; r < 16; ++r) ps += p0[r];
; #pragma unroll
;   for (int r = 0; r < 16; ++r) ps += p1[r];
;   { auto rr = __builtin_amdgcn_permlane32_swap(__float_as_uint(ps), __float_as_uint(ps), false, false);
;     ps = __uint_as_float(rr[0]) + __uint_as_float(rr[1]); }
;   l_reg = l_reg * alpha + ps;
;     ...
;   PK4(p0, 0, pa0); PK4(p0, 8, pa1); PK4(p1, 0, pa2); PK4(p1, 8, pa3);
;     ...
; }
; __device__ __forceinline__ void qkt(f32x16& p0, f32x16& p1, const char* Ks, const bf16x8* qr, const char* qrl, int r32, int hi) {
;   p0 = f32x16{}; p1 = f32x16{};
; #pragma unroll
;   for (int d0 = 0; d0 < 8; ++d0) { int cb = (d0 * 16 + hi * 8) * 2;
;     bf16x8 b0 = *reinterpret_cast<const bf16x8*>(Ks + KSWZ(r32, cb));
;     bf16x8 b1 = *reinterpret_cast<const bf16x8*>(Ks + KSWZ(32 + r32, cb));
;     p0 = __builtin_amdgcn_mfma_f32_32x32x16_bf16(b0, qr[d0], p0, 0, 0, 0);
;     p1 = __builtin_amdgcn_mfma_f32_32x32x16_bf16(b1, qr[d0], p1, 0, 0, 0); }
; #pragma unroll
;   for (int d0 = 8; d0 < 12; ++d0) { int cb = (d0 * 16 + hi * 8) * 2;
;     bf16x8 b0 = *reinterpret_cast<const bf16x8*>(Ks + KSWZ(r32, cb));
;     bf16x8 b1 = *reinterpret_cast<const bf16x8*>(Ks + KSWZ(32 + r32, cb));
;     bf16x8 qf = *reinterpret_cast<const bf16x8*>(qrl + (((2 * (d0 - 8) + hi) ^ ((r32 >> 1) & 7)) << 4));
;     p0 = __builtin_amdgcn_mfma_f32_32x32x16_bf16(b0, qf, p0, 0, 0, 0);
;     p1 = __builtin_amdgcn_mfma_f32_32x32x16_bf16(b1, qf, p1, 0, 0, 0); }
; }
.LBB0_1151:
	s_sub_i32 s30, s76, 1
	s_cmp_eq_u32 s76, 0
	s_cselect_b32 s30, 2, s30
	s_add_i32 s18, s76, 1
	s_cmp_lg_u32 s76, 2
	s_cselect_b32 s18, s18, 0
	s_lshl_b32 s31, s30, 14
	v_add_u32_e32 v180, s31, v178
	ds_read_b128 v[232:235], v199 offset:36864
	ds_read_b128 v[236:239], v199 offset:49152
	ds_read_b128 v[240:243], v205 offset:36864
	ds_read_b128 v[248:251], v205 offset:49152
	v_exp_f32_e32 v162, v162
	v_add_f32_e32 v211, v225, v228
	v_exp_f32_e32 v163, v163
	v_add_f32_e32 v211, v226, v211
	v_exp_f32_e32 v160, v160
	s_waitcnt lgkmcnt(2)
	v_mfma_f32_32x32x16_bf16 v[80:95], v[232:235], v[124:127], 0
	ds_read_b128 v[232:235], v206 offset:36864
	v_add_f32_e32 v211, v229, v211
	v_exp_f32_e32 v161, v161
	v_add_f32_e32 v211, v227, v211
	v_exp_f32_e32 v158, v158
	v_mfma_f32_32x32x16_bf16 v[64:79], v[236:239], v[124:127], 0
	ds_read_b128 v[236:239], v206 offset:49152
	v_add_f32_e32 v211, v230, v211
	v_exp_f32_e32 v159, v159
	v_add_f32_e32 v211, v223, v211
	v_exp_f32_e32 v156, v156
	s_waitcnt lgkmcnt(2)
	v_mfma_f32_32x32x16_bf16 v[80:95], v[240:243], v[120:123], v[80:95]
	ds_read_b128 v[240:243], v208 offset:36864
	v_add_f32_e32 v211, v224, v211
	v_exp_f32_e32 v157, v157
	v_add_f32_e32 v211, v219, v211
	v_exp_f32_e32 v154, v154
	v_mfma_f32_32x32x16_bf16 v[64:79], v[248:251], v[120:123], v[64:79]
	ds_read_b128 v[248:251], v208 offset:49152
	v_add_f32_e32 v211, v221, v211
	v_exp_f32_e32 v155, v155
	v_add_f32_e32 v211, v220, v211
	v_exp_f32_e32 v152, v152
	s_waitcnt lgkmcnt(2)
	v_mfma_f32_32x32x16_bf16 v[80:95], v[232:235], v[116:119], v[80:95]
	ds_read_b128 v[232:235], v207 offset:36864
	v_add_f32_e32 v211, v222, v211
	v_exp_f32_e32 v153, v153
	v_add_f32_e32 v211, v215, v211
	v_exp_f32_e32 v150, v150
	v_mfma_f32_32x32x16_bf16 v[64:79], v[236:239], v[116:119], v[64:79]
	ds_read_b128 v[236:239], v207 offset:49152
	v_add_f32_e32 v211, v217, v211
	v_exp_f32_e32 v151, v151
	v_add_f32_e32 v211, v216, v211
	v_exp_f32_e32 v148, v148
	s_waitcnt lgkmcnt(2)
	v_mfma_f32_32x32x16_bf16 v[80:95], v[240:243], v[112:115], v[80:95]
	ds_read_b128 v[240:243], v204 offset:36864
	v_add_f32_e32 v211, v218, v211
	v_exp_f32_e32 v149, v149
	v_add_f32_e32 v212, v162, v163
	v_add_f32_e32 v212, v160, v212
	v_add_f32_e32 v212, v161, v212
	v_mfma_f32_32x32x16_bf16 v[64:79], v[248:251], v[112:115], v[64:79]
	ds_read_b128 v[248:251], v204 offset:49152
	v_add_f32_e32 v212, v158, v212
	v_add_f32_e32 v212, v159, v212
	v_add_f32_e32 v212, v156, v212
	v_add_f32_e32 v212, v157, v212
	v_add_f32_e32 v212, v154, v212
	v_add_f32_e32 v212, v155, v212
	s_waitcnt lgkmcnt(2)
	v_mfma_f32_32x32x16_bf16 v[80:95], v[232:235], v[108:111], v[80:95]
	ds_read_b128 v[232:235], v203 offset:36864
	v_add_f32_e32 v212, v152, v212
	v_add_f32_e32 v212, v153, v212
	v_add_f32_e32 v212, v150, v212
	v_add_f32_e32 v212, v151, v212
	v_add_f32_e32 v212, v148, v212
	v_add_f32_e32 v212, v149, v212
	v_mfma_f32_32x32x16_bf16 v[64:79], v[236:239], v[108:111], v[64:79]
	ds_read_b128 v[236:239], v203 offset:49152
	v_add_f32_e32 v211, v211, v212
	v_mov_b32_e32 v212, v211
	s_lshl_b32 s19, s18, 14
	v_add_u32_e32 v231, s19, v183
	s_waitcnt vmcnt(0)
	ds_write_b128 v231, v[140:143]
	v_add_u32_e32 v140, s19, v184
	ds_write_b128 v140, v[144:147]
	ds_write_b128 v185, v[136:139] offset:12288
	s_waitcnt lgkmcnt(5)
	v_mfma_f32_32x32x16_bf16 v[80:95], v[240:243], v[104:107], v[80:95]
	ds_read_b128 v[240:243], v200 offset:36864
	ds_write_b128 v185, v[132:135] offset:24576
	s_mov_b32 s18, 0xfffa0000
	ds_write_b128 v186, v[128:131] offset:12288
	v_add_co_u32_e32 v128, vcc, s18, v168
	s_mov_b32 s18, 0xfffc0000
	s_nop 0
	v_addc_co_u32_e32 v129, vcc, -1, v169, vcc
	v_add_co_u32_e32 v130, vcc, s18, v168
	s_movk_i32 s18, 0xe000
	s_nop 0
	v_addc_co_u32_e32 v131, vcc, -1, v169, vcc
	v_mfma_f32_32x32x16_bf16 v[64:79], v[248:251], v[104:107], v[64:79]
	ds_read_b128 v[248:251], v200 offset:49152
	global_load_dwordx4 v[140:143], v[128:129], off
	global_load_dwordx4 v[136:139], v[128:129], off offset:-256
	global_load_dwordx4 v[144:147], v[130:131], off
	global_load_dwordx4 v[132:135], v[130:131], off offset:-256
	v_add_co_u32_e32 v128, vcc, s18, v166
	s_nop 1
	v_addc_co_u32_e32 v129, vcc, -1, v167, vcc
	s_waitcnt lgkmcnt(7)
; __device__ __forceinline__ void partialSM(f32x16& p0, f32x16& p1, float& m_reg, float& mn, float& alpha) {
;   constexpr float C = SCALE * 1.4426950408889634f;
;   float pmax = p0[0];
; #pragma unroll
;   for (int r = 1; r < 16; ++r) pmax = fmaxf(pmax, p0[r]);
; #pragma unroll
;   for (int r = 0; r < 16; ++r) pmax = fmaxf(pmax, p1[r]);
;   { auto rr = __builtin_amdgcn_permlane32_swap(__float_as_uint(pmax), __float_as_uint(pmax), false, false);
;     pmax = fmaxf(__uint_as_float(rr[0]), __uint_as_float(rr[1])); }
;   if (__builtin_expect(__all(pmax - m_reg <= THR / SCALE), 1)) { mn = m_reg; alpha = 1.f; }
;   else { mn = fmaxf(m_reg, pmax); alpha = __builtin_amdgcn_exp2f((m_reg - mn) * C); m_reg = mn; }
;   float mnC = -mn * C;
; #pragma unroll
;   for (int r = 0; r < 16; ++r) p0[r] = fmaf(p0[r], C, mnC);
; #pragma unroll
;   for (int r = 0; r < 16; ++r) p1[r] = fmaf(p1[r], C, mnC);
; #pragma unroll
;   for (int r = 0; r < 16; ++r) p0[r] = __builtin_amdgcn_exp2f(p0[r]);
; }
; __device__ __forceinline__ void qkt(f32x16& p0, f32x16& p1, const char* Ks, const bf16x8* qr, const char* qrl, int r32, int hi) {
;   p0 = f32x16{}; p1 = f32x16{};
; #pragma unroll
;   for (int d0 = 0; d0 < 8; ++d0) { int cb = (d0 * 16 + hi * 8) * 2;
;     bf16x8 b0 = *reinterpret_cast<const bf16x8*>(Ks + KSWZ(r32, cb));
;     bf16x8 b1 = *reinterpret_cast<const bf16x8*>(Ks + KSWZ(32 + r32, cb));
;     p0 = __builtin_amdgcn_mfma_f32_32x32x16_bf16(b0, qr[d0], p0, 0, 0, 0);
;     p1 = __builtin_amdgcn_mfma_f32_32x32x16_bf16(b1, qr[d0], p1, 0, 0, 0); }
; #pragma unroll
;   for (int d0 = 8; d0 < 12; ++d0) { int cb = (d0 * 16 + hi * 8) * 2;
;     bf16x8 b0 = *reinterpret_cast<const bf16x8*>(Ks + KSWZ(r32, cb));
;     bf16x8 b1 = *reinterpret_cast<const bf16x8*>(Ks + KSWZ(32 + r32, cb));
;     bf16x8 qf = *reinterpret_cast<const bf16x8*>(qrl + (((2 * (d0 - 8) + hi) ^ ((r32 >> 1) & 7)) << 4));
;     p0 = __builtin_amdgcn_mfma_f32_32x32x16_bf16(b0, qf, p0, 0, 0, 0);
;     p1 = __builtin_amdgcn_mfma_f32_32x32x16_bf16(b1, qf, p1, 0, 0, 0); }
; }
; __device__ __forceinline__ int v_st(int k, int c) { const int kk = (k & ~0xC) | ((k & 4) << 1) | ((k & 8) >> 1); return ((kk >> 3) * 4 + (c >> 5)) * 512 + ((kk & 7) * 32 + (c & 31)) * 2; }
; __device__ __forceinline__ int v_rd_base(int lane) { return ((lane & 3) << 3) | (((lane >> 2) & 3) << 6) | (((lane >> 4) & 1) << 5) | (((lane >> 5) & 1) << 8); }
	v_mfma_f32_32x32x16_bf16 v[80:95], v[232:235], v[100:103], v[80:95]
	ds_read_b128 v[232:235], v191 offset:36864
	global_load_dwordx4 v[128:131], v[128:129], off
	v_cvt_pk_bf16_f32 v158, v158, v159
	v_cvt_pk_bf16_f32 v159, v156, v157
	v_permlane32_swap_b32_e32 v211, v212
	v_cvt_pk_bf16_f32 v156, v162, v163
	v_cvt_pk_bf16_f32 v157, v160, v161
	v_mfma_f32_32x32x16_bf16 v[64:79], v[236:239], v[100:103], v[64:79]
	ds_read_b128 v[236:239], v202 offset:49152
	v_cvt_pk_bf16_f32 v160, v154, v155
	v_cvt_pk_bf16_f32 v161, v152, v153
	v_cvt_pk_bf16_f32 v162, v150, v151
	v_cvt_pk_bf16_f32 v163, v148, v149
	v_add_f32_e32 v211, v211, v212
	v_cvt_pk_bf16_f32 v148, v225, v228
	s_waitcnt lgkmcnt(2)
	v_mfma_f32_32x32x16_bf16 v[80:95], v[240:243], v[96:99], v[80:95]
	ds_read_b128 v[240:243], v182
	v_cvt_pk_bf16_f32 v149, v226, v229
	v_cvt_pk_bf16_f32 v150, v227, v230
	v_cvt_pk_bf16_f32 v151, v223, v224
	v_cvt_pk_bf16_f32 v152, v219, v221
	v_cvt_pk_bf16_f32 v153, v220, v222
	v_cvt_pk_bf16_f32 v154, v215, v217
	v_mfma_f32_32x32x16_bf16 v[64:79], v[248:251], v[96:99], v[64:79]
	ds_read_b128 v[248:251], v198 offset:36864
	v_cvt_pk_bf16_f32 v155, v216, v218
	v_fma_f32 v176, v209, v176, v211
	s_waitcnt lgkmcnt(1)
	v_mfma_f32_32x32x16_bf16 v[80:95], v[232:235], v[240:243], v[80:95]
	ds_read_b128 v[232:235], v201 offset:49152
	v_mfma_f32_32x32x16_bf16 v[64:79], v[236:239], v[240:243], v[64:79]
	ds_read_b128 v[236:239], v181
	ds_read_b128 v[240:243], v187 offset:36864
	s_waitcnt lgkmcnt(1)
	v_mfma_f32_32x32x16_bf16 v[80:95], v[248:251], v[236:239], v[80:95]
	ds_read_b128 v[248:251], v189 offset:49152
	v_mfma_f32_32x32x16_bf16 v[64:79], v[232:235], v[236:239], v[64:79]
	ds_read_b128 v[232:235], v179
	ds_read_b128 v[236:239], v188 offset:36864
	s_waitcnt lgkmcnt(1)
	v_mfma_f32_32x32x16_bf16 v[80:95], v[240:243], v[232:235], v[80:95]
	ds_read_b128 v[240:243], v190 offset:49152
	v_mfma_f32_32x32x16_bf16 v[64:79], v[248:251], v[232:235], v[64:79]
	ds_read_b128 v[248:251], v177
	ds_read_b64_tr_b16 v[232:233], v180 offset:0
	ds_read_b64_tr_b16 v[234:235], v180 offset:2048
	s_waitcnt lgkmcnt(2)
	v_mfma_f32_32x32x16_bf16 v[80:95], v[236:239], v[248:251], v[80:95]
	ds_read_b64_tr_b16 v[236:237], v180 offset:512
	ds_read_b64_tr_b16 v[238:239], v180 offset:2560
	v_mfma_f32_32x32x16_bf16 v[64:79], v[240:243], v[248:251], v[64:79]
	ds_read_b64_tr_b16 v[240:241], v180 offset:1024
	ds_read_b64_tr_b16 v[242:243], v180 offset:3072
	ds_read_b64_tr_b16 v[248:249], v180 offset:1536
	ds_read_b64_tr_b16 v[250:251], v180 offset:3584
	s_waitcnt lgkmcnt(4)
	v_mfma_f32_32x32x16_bf16 v[32:47], v[148:151], v[232:235], v[32:47]
	ds_read_b64_tr_b16 v[232:233], v180 offset:4096
	ds_read_b64_tr_b16 v[234:235], v180 offset:6144
	v_mfma_f32_32x32x16_bf16 v[48:63], v[148:151], v[236:239], v[48:63]
	ds_read_b64_tr_b16 v[236:237], v180 offset:4608
	ds_read_b64_tr_b16 v[238:239], v180 offset:6656
	v_max3_f32 v194, v80, v81, v82
	v_max3_f32 v195, v64, v65, v66
	v_max3_f32 v194, v194, v83, v84
	v_max3_f32 v195, v195, v67, v68
	v_max3_f32 v194, v194, v85, v86
	v_max3_f32 v195, v195, v69, v70
	s_waitcnt lgkmcnt(4)
	v_mfma_f32_32x32x16_bf16 v[16:31], v[148:151], v[240:243], v[16:31]
	ds_read_b64_tr_b16 v[240:241], v180 offset:5120
	ds_read_b64_tr_b16 v[242:243], v180 offset:7168
	v_max3_f32 v194, v194, v87, v88
	v_max3_f32 v195, v195, v71, v72
	v_max3_f32 v194, v194, v89, v90
	v_max3_f32 v195, v195, v73, v74
	v_max3_f32 v194, v194, v91, v92
	v_max3_f32 v195, v195, v75, v76
	v_mfma_f32_32x32x16_bf16 v[0:15], v[148:151], v[248:251], v[0:15]
	ds_read_b64_tr_b16 v[248:249], v180 offset:5632
	ds_read_b64_tr_b16 v[250:251], v180 offset:7680
	v_max3_f32 v194, v194, v93, v94
	v_max3_f32 v195, v195, v77, v78
	v_max3_f32 v194, v194, v95, v195
	v_max_f32_e32 v194, v194, v79
	v_mov_b32_e32 v195, v194
	s_nop 1
	s_waitcnt lgkmcnt(4)
	v_mfma_f32_32x32x16_bf16 v[32:47], v[152:155], v[232:235], v[32:47]
	ds_read_b64_tr_b16 v[232:233], v180 offset:8192
	ds_read_b64_tr_b16 v[234:235], v180 offset:10240
	v_permlane32_swap_b32_e32 v194, v195
	v_max_f32_e32 v194, v194, v195
	v_sub_f32_e32 v195, v194, v210
	v_cmp_ge_f32_e32 vcc, s15, v195
	v_mfma_f32_32x32x16_bf16 v[48:63], v[152:155], v[236:239], v[48:63]
	ds_read_b64_tr_b16 v[236:237], v180 offset:8704
	ds_read_b64_tr_b16 v[238:239], v180 offset:10752
	s_cmp_eq_u64 vcc, exec
	s_cselect_b64 s[40:41], -1, 0
	s_cbranch_scc1 .Lattn_fast1p
	v_max_f32_e32 v194, v210, v194
	v_sub_f32_e32 v195, v210, v194
	v_mul_f32_e32 v195, 0x3dd53b94, v195
	v_exp_f32_e32 v214, v195
	v_mov_b32_e32 v210, v194
	s_branch .Lattn_join1p

; __device__ __forceinline__ void partialSM(f32x16& p0, f32x16& p1, float& m_reg, float& mn, float& alpha) {
;     ...
;   for (int r = 0; r < 16; ++r) p0[r] = fmaf(p0[r], C, mnC);
; #pragma unroll
;   for (int r = 0; r < 16; ++r) p1[r] = fmaf(p1[r], C, mnC);
; #pragma unroll
;   for (int r = 0; r < 16; ++r) p0[r] = __builtin_amdgcn_exp2f(p0[r]);
; }
; __device__ __forceinline__ void finishSM(f32x16& p0, f32x16& p1, float alpha, float& l_reg, bf16x8& pa0, bf16x8& pa1, bf16x8& pa2, bf16x8& pa3) {
; #pragma unroll
;   for (int r = 0; r < 16; ++r) p1[r] = __builtin_amdgcn_exp2f(p1[r]);
;   float ps = 0;
; #pragma unroll
;   for (int r = 0; r < 16; ++r) ps += p0[r];
; #pragma unroll
;   for (int r = 0; r < 16; ++r) ps += p1[r];
;   { auto rr = __builtin_amdgcn_permlane32_swap(__float_as_uint(ps), __float_as_uint(ps), false, false);
;     ps = __uint_as_float(rr[0]) + __uint_as_float(rr[1]); }
;   l_reg = l_reg * alpha + ps;
;     ...
;   PK4(p0, 0, pa0); PK4(p0, 8, pa1); PK4(p1, 0, pa2); PK4(p1, 8, pa3);
;     ...
; }
; __device__ __forceinline__ void qkt(f32x16& p0, f32x16& p1, const char* Ks, const bf16x8* qr, const char* qrl, int r32, int hi) {
;   p0 = f32x16{}; p1 = f32x16{};
; #pragma unroll
;   for (int d0 = 0; d0 < 8; ++d0) { int cb = (d0 * 16 + hi * 8) * 2;
;     bf16x8 b0 = *reinterpret_cast<const bf16x8*>(Ks + KSWZ(r32, cb));
;     bf16x8 b1 = *reinterpret_cast<const bf16x8*>(Ks + KSWZ(32 + r32, cb));
;     p0 = __builtin_amdgcn_mfma_f32_32x32x16_bf16(b0, qr[d0], p0, 0, 0, 0);
;     p1 = __builtin_amdgcn_mfma_f32_32x32x16_bf16(b1, qr[d0], p1, 0, 0, 0); }
; #pragma unroll
;   for (int d0 = 8; d0 < 12; ++d0) { int cb = (d0 * 16 + hi * 8) * 2;
;     bf16x8 b0 = *reinterpret_cast<const bf16x8*>(Ks + KSWZ(r32, cb));
;     bf16x8 b1 = *reinterpret_cast<const bf16x8*>(Ks + KSWZ(32 + r32, cb));
;     bf16x8 qf = *reinterpret_cast<const bf16x8*>(qrl + (((2 * (d0 - 8) + hi) ^ ((r32 >> 1) & 7)) << 4));
;     p0 = __builtin_amdgcn_mfma_f32_32x32x16_bf16(b0, qf, p0, 0, 0, 0);
;     p1 = __builtin_amdgcn_mfma_f32_32x32x16_bf16(b1, qf, p1, 0, 0, 0); }
; }
; __device__ __forceinline__ int v_st(int k, int c) { const int kk = (k & ~0xC) | ((k & 4) << 1) | ((k & 8) >> 1); return ((kk >> 3) * 4 + (c >> 5)) * 512 + ((kk & 7) * 32 + (c & 31)) * 2; }
.Lattn_join1p:
	v_mul_f32_e32 v194, 0xbdd53b94, v210
	v_fmamk_f32 v225, v80, 0x3dd53b94, v194
	v_fmamk_f32 v228, v81, 0x3dd53b94, v194
	s_waitcnt lgkmcnt(4)
	v_mfma_f32_32x32x16_bf16 v[16:31], v[152:155], v[240:243], v[16:31]
	ds_read_b64_tr_b16 v[240:241], v180 offset:9216
	ds_read_b64_tr_b16 v[242:243], v180 offset:11264
	v_fmamk_f32 v226, v82, 0x3dd53b94, v194
	v_fmamk_f32 v229, v83, 0x3dd53b94, v194
	v_fmamk_f32 v150, v76, 0x3dd53b94, v194
	v_fmamk_f32 v151, v77, 0x3dd53b94, v194
	v_fmamk_f32 v148, v78, 0x3dd53b94, v194
	v_fmamk_f32 v149, v79, 0x3dd53b94, v194
	v_mfma_f32_32x32x16_bf16 v[0:15], v[152:155], v[248:251], v[0:15]
	ds_read_b64_tr_b16 v[248:249], v180 offset:9728
	ds_read_b64_tr_b16 v[250:251], v180 offset:11776
	v_fmamk_f32 v227, v84, 0x3dd53b94, v194
	v_fmamk_f32 v230, v85, 0x3dd53b94, v194
	v_fmamk_f32 v223, v86, 0x3dd53b94, v194
	v_fmamk_f32 v224, v87, 0x3dd53b94, v194
	v_fmamk_f32 v154, v72, 0x3dd53b94, v194
	v_fmamk_f32 v155, v73, 0x3dd53b94, v194
	s_waitcnt lgkmcnt(4)
	v_mfma_f32_32x32x16_bf16 v[32:47], v[156:159], v[232:235], v[32:47]
	ds_read_b64_tr_b16 v[232:233], v180 offset:12288
	ds_read_b64_tr_b16 v[234:235], v180 offset:14336
	v_fmamk_f32 v152, v74, 0x3dd53b94, v194
	v_fmamk_f32 v153, v75, 0x3dd53b94, v194
	v_fmamk_f32 v219, v88, 0x3dd53b94, v194
	v_fmamk_f32 v221, v89, 0x3dd53b94, v194
	v_fmamk_f32 v220, v90, 0x3dd53b94, v194
	v_fmamk_f32 v222, v91, 0x3dd53b94, v194
	v_mfma_f32_32x32x16_bf16 v[48:63], v[156:159], v[236:239], v[48:63]
	ds_read_b64_tr_b16 v[236:237], v180 offset:12800
	ds_read_b64_tr_b16 v[238:239], v180 offset:14848
	s_waitcnt lgkmcnt(4)
	v_mfma_f32_32x32x16_bf16 v[16:31], v[156:159], v[240:243], v[16:31]
	ds_read_b64_tr_b16 v[240:241], v180 offset:13312
	ds_read_b64_tr_b16 v[242:243], v180 offset:15360
	v_mfma_f32_32x32x16_bf16 v[0:15], v[156:159], v[248:251], v[0:15]
	ds_read_b64_tr_b16 v[248:249], v180 offset:13824
	ds_read_b64_tr_b16 v[250:251], v180 offset:15872
	v_fmamk_f32 v158, v68, 0x3dd53b94, v194
	v_fmamk_f32 v159, v69, 0x3dd53b94, v194
	v_fmamk_f32 v156, v70, 0x3dd53b94, v194
	v_fmamk_f32 v157, v71, 0x3dd53b94, v194
	v_fmamk_f32 v215, v92, 0x3dd53b94, v194
	v_fmamk_f32 v217, v93, 0x3dd53b94, v194
	s_waitcnt lgkmcnt(0)
	s_barrier
	v_mfma_f32_32x32x16_bf16 v[32:47], v[160:163], v[232:235], v[32:47]
	ds_read_b128 v[232:235], v199 offset:12288
	v_fmamk_f32 v216, v94, 0x3dd53b94, v194
	v_fmamk_f32 v218, v95, 0x3dd53b94, v194
	v_mfma_f32_32x32x16_bf16 v[48:63], v[160:163], v[236:239], v[48:63]
	ds_read_b128 v[236:239], v199 offset:24576
	v_mfma_f32_32x32x16_bf16 v[16:31], v[160:163], v[240:243], v[16:31]
	ds_read_b128 v[240:243], v205 offset:12288
	v_mfma_f32_32x32x16_bf16 v[0:15], v[160:163], v[248:251], v[0:15]
	ds_read_b128 v[248:251], v205 offset:24576
	v_fmamk_f32 v162, v64, 0x3dd53b94, v194
	v_fmamk_f32 v163, v65, 0x3dd53b94, v194
	v_fmamk_f32 v160, v66, 0x3dd53b94, v194
	v_fmamk_f32 v161, v67, 0x3dd53b94, v194
	s_and_b64 vcc, exec, s[40:41]
	s_cbranch_vccnz .Lattn_skip_rs1p
	s_and_saveexec_b64 s[18:19], s[38:39]
	ds_write_b32 v175, v214 offset:128
	s_or_b64 exec, exec, s[18:19]
	s_waitcnt lgkmcnt(0)
	v_add_u32_e32 v194, v173, v164
	ds_read_b128 v[64:67], v194 offset:224
	ds_read_b128 v[68:71], v194 offset:192
	ds_read_b128 v[72:75], v194 offset:160
	ds_read_b128 v[76:79], v194 offset:128
	s_waitcnt lgkmcnt(0)
	v_pk_mul_f32 v[44:45], v[44:45], v[64:65]
	v_pk_mul_f32 v[46:47], v[46:47], v[66:67]
	v_pk_mul_f32 v[40:41], v[40:41], v[68:69]
	v_pk_mul_f32 v[42:43], v[42:43], v[70:71]
	v_pk_mul_f32 v[36:37], v[36:37], v[72:73]
	v_pk_mul_f32 v[38:39], v[38:39], v[74:75]
	v_pk_mul_f32 v[32:33], v[32:33], v[76:77]
	v_pk_mul_f32 v[34:35], v[34:35], v[78:79]
	v_pk_mul_f32 v[60:61], v[60:61], v[64:65]
	v_pk_mul_f32 v[62:63], v[62:63], v[66:67]
	v_pk_mul_f32 v[56:57], v[56:57], v[68:69]
	v_pk_mul_f32 v[58:59], v[58:59], v[70:71]
	v_pk_mul_f32 v[52:53], v[52:53], v[72:73]
	v_pk_mul_f32 v[54:55], v[54:55], v[74:75]
	v_pk_mul_f32 v[48:49], v[48:49], v[76:77]
	v_pk_mul_f32 v[50:51], v[50:51], v[78:79]
	v_pk_mul_f32 v[28:29], v[28:29], v[64:65]
	v_pk_mul_f32 v[30:31], v[30:31], v[66:67]
	v_pk_mul_f32 v[24:25], v[24:25], v[68:69]
	v_pk_mul_f32 v[26:27], v[26:27], v[70:71]
	v_pk_mul_f32 v[20:21], v[20:21], v[72:73]
	v_pk_mul_f32 v[22:23], v[22:23], v[74:75]
	v_pk_mul_f32 v[16:17], v[16:17], v[76:77]
	v_pk_mul_f32 v[18:19], v[18:19], v[78:79]
	v_pk_mul_f32 v[12:13], v[12:13], v[64:65]
	v_pk_mul_f32 v[14:15], v[14:15], v[66:67]
	v_pk_mul_f32 v[8:9], v[8:9], v[68:69]
	v_pk_mul_f32 v[10:11], v[10:11], v[70:71]
	v_pk_mul_f32 v[4:5], v[4:5], v[72:73]
	v_pk_mul_f32 v[6:7], v[6:7], v[74:75]
	v_pk_mul_f32 v[0:1], v[0:1], v[76:77]
	v_pk_mul_f32 v[2:3], v[2:3], v[78:79]
; __device__ __forceinline__ void finishSM(f32x16& p0, f32x16& p1, float alpha, float& l_reg, bf16x8& pa0, bf16x8& pa1, bf16x8& pa2, bf16x8& pa3) {
; #pragma unroll
;   for (int r = 0; r < 16; ++r) p1[r] = __builtin_amdgcn_exp2f(p1[r]);
;   float ps = 0;
; #pragma unroll
;   for (int r = 0; r < 16; ++r) ps += p0[r];
; #pragma unroll
;   for (int r = 0; r < 16; ++r) ps += p1[r];
;   { auto rr = __builtin_amdgcn_permlane32_swap(__float_as_uint(ps), __float_as_uint(ps), false, false);
;     ps = __uint_as_float(rr[0]) + __uint_as_float(rr[1]); }
;   l_reg = l_reg * alpha + ps;
;     ...
;   PK4(p0, 0, pa0); PK4(p0, 8, pa1); PK4(p1, 0, pa2); PK4(p1, 8, pa3);
;     ...
; }
; __device__ __forceinline__ void qkt(f32x16& p0, f32x16& p1, const char* Ks, const bf16x8* qr, const char* qrl, int r32, int hi) {
;   p0 = f32x16{}; p1 = f32x16{};
; #pragma unroll
;   for (int d0 = 0; d0 < 8; ++d0) { int cb = (d0 * 16 + hi * 8) * 2;
;     bf16x8 b0 = *reinterpret_cast<const bf16x8*>(Ks + KSWZ(r32, cb));
;     bf16x8 b1 = *reinterpret_cast<const bf16x8*>(Ks + KSWZ(32 + r32, cb));
;     p0 = __builtin_amdgcn_mfma_f32_32x32x16_bf16(b0, qr[d0], p0, 0, 0, 0);
;     p1 = __builtin_amdgcn_mfma_f32_32x32x16_bf16(b1, qr[d0], p1, 0, 0, 0); }
; #pragma unroll
;   for (int d0 = 8; d0 < 12; ++d0) { int cb = (d0 * 16 + hi * 8) * 2;
;     bf16x8 b0 = *reinterpret_cast<const bf16x8*>(Ks + KSWZ(r32, cb));
;     bf16x8 b1 = *reinterpret_cast<const bf16x8*>(Ks + KSWZ(32 + r32, cb));
;     bf16x8 qf = *reinterpret_cast<const bf16x8*>(qrl + (((2 * (d0 - 8) + hi) ^ ((r32 >> 1) & 7)) << 4));
;     p0 = __builtin_amdgcn_mfma_f32_32x32x16_bf16(b0, qf, p0, 0, 0, 0);
;     p1 = __builtin_amdgcn_mfma_f32_32x32x16_bf16(b1, qf, p1, 0, 0, 0); }
; }
.Lattn_skip_rs1p:
	v_lshl_add_u32 v231, s76, 14, v178
	v_exp_f32_e32 v225, v225
	v_exp_f32_e32 v228, v228
	v_exp_f32_e32 v226, v226
	v_add_f32_e32 v211, v225, v228
	s_waitcnt lgkmcnt(2)
	v_mfma_f32_32x32x16_bf16 v[80:95], v[232:235], v[124:127], 0
	ds_read_b128 v[232:235], v206 offset:12288
	v_exp_f32_e32 v229, v229
	v_add_f32_e32 v211, v226, v211
	v_exp_f32_e32 v227, v227
	v_add_f32_e32 v211, v229, v211
	v_mfma_f32_32x32x16_bf16 v[64:79], v[236:239], v[124:127], 0
	ds_read_b128 v[236:239], v206 offset:24576
	v_exp_f32_e32 v230, v230
	v_add_f32_e32 v211, v227, v211
	v_exp_f32_e32 v223, v223
	v_add_f32_e32 v211, v230, v211
	s_waitcnt lgkmcnt(2)
	v_mfma_f32_32x32x16_bf16 v[80:95], v[240:243], v[120:123], v[80:95]
	ds_read_b128 v[240:243], v208 offset:12288
	v_exp_f32_e32 v224, v224
	v_add_f32_e32 v211, v223, v211
	v_exp_f32_e32 v219, v219
	v_add_f32_e32 v211, v224, v211
	v_mfma_f32_32x32x16_bf16 v[64:79], v[248:251], v[120:123], v[64:79]
	ds_read_b128 v[248:251], v208 offset:24576
	v_exp_f32_e32 v221, v221
	v_add_f32_e32 v211, v219, v211
	v_exp_f32_e32 v220, v220
	v_add_f32_e32 v211, v221, v211
	s_waitcnt lgkmcnt(2)
	v_mfma_f32_32x32x16_bf16 v[80:95], v[232:235], v[116:119], v[80:95]
	ds_read_b128 v[232:235], v207 offset:12288
	v_exp_f32_e32 v222, v222
	v_add_f32_e32 v211, v220, v211
	v_exp_f32_e32 v215, v215
	v_add_f32_e32 v211, v222, v211
	v_mfma_f32_32x32x16_bf16 v[64:79], v[236:239], v[116:119], v[64:79]
	ds_read_b128 v[236:239], v207 offset:24576
	v_exp_f32_e32 v217, v217
	v_add_f32_e32 v211, v215, v211
	v_exp_f32_e32 v216, v216
	v_add_f32_e32 v211, v217, v211
	s_waitcnt lgkmcnt(2)
	v_mfma_f32_32x32x16_bf16 v[80:95], v[240:243], v[112:115], v[80:95]
	ds_read_b128 v[240:243], v204 offset:12288
	v_exp_f32_e32 v218, v218
	v_add_f32_e32 v211, v216, v211
	v_exp_f32_e32 v162, v162
	v_add_f32_e32 v211, v218, v211
	v_mfma_f32_32x32x16_bf16 v[64:79], v[248:251], v[112:115], v[64:79]
	ds_read_b128 v[248:251], v204 offset:24576
	v_exp_f32_e32 v163, v163
	v_exp_f32_e32 v160, v160
	v_exp_f32_e32 v161, v161
	s_waitcnt lgkmcnt(2)
	v_mfma_f32_32x32x16_bf16 v[80:95], v[232:235], v[108:111], v[80:95]
	ds_read_b128 v[232:235], v203 offset:12288
	v_exp_f32_e32 v158, v158
	v_exp_f32_e32 v159, v159
	v_exp_f32_e32 v156, v156
	v_mfma_f32_32x32x16_bf16 v[64:79], v[236:239], v[108:111], v[64:79]
	ds_read_b128 v[236:239], v203 offset:24576
	v_exp_f32_e32 v157, v157
	v_exp_f32_e32 v154, v154
	v_exp_f32_e32 v155, v155
	s_waitcnt lgkmcnt(2)
	v_mfma_f32_32x32x16_bf16 v[80:95], v[240:243], v[104:107], v[80:95]
	ds_read_b128 v[240:243], v200 offset:12288
	v_exp_f32_e32 v152, v152
	v_exp_f32_e32 v153, v153
	v_exp_f32_e32 v150, v150
	v_mfma_f32_32x32x16_bf16 v[64:79], v[248:251], v[104:107], v[64:79]
	ds_read_b128 v[248:251], v200 offset:24576
	v_exp_f32_e32 v151, v151
	v_exp_f32_e32 v148, v148
	v_exp_f32_e32 v149, v149
	s_waitcnt lgkmcnt(2)
	v_mfma_f32_32x32x16_bf16 v[80:95], v[232:235], v[100:103], v[80:95]
	ds_read_b128 v[232:235], v191 offset:12288
	v_add_f32_e32 v212, v162, v163
	v_add_f32_e32 v212, v160, v212
	v_add_f32_e32 v212, v161, v212
	v_add_f32_e32 v212, v158, v212
	v_add_f32_e32 v212, v159, v212
	v_add_f32_e32 v212, v156, v212
	v_mfma_f32_32x32x16_bf16 v[64:79], v[236:239], v[100:103], v[64:79]
	ds_read_b128 v[236:239], v202 offset:24576
	v_add_f32_e32 v212, v157, v212
	v_add_f32_e32 v212, v154, v212
	v_add_f32_e32 v212, v155, v212
	v_add_f32_e32 v212, v152, v212
	v_add_f32_e32 v212, v153, v212
	v_add_f32_e32 v212, v150, v212
	s_waitcnt lgkmcnt(2)
	v_mfma_f32_32x32x16_bf16 v[80:95], v[240:243], v[96:99], v[80:95]
	ds_read_b128 v[240:243], v182
	v_add_f32_e32 v212, v151, v212
	v_add_f32_e32 v212, v148, v212
	v_add_f32_e32 v212, v149, v212
	v_add_f32_e32 v211, v211, v212
	v_mov_b32_e32 v212, v211
	v_add_u32_e32 v194, s31, v183
	s_waitcnt vmcnt(4)
	v_mfma_f32_32x32x16_bf16 v[64:79], v[248:251], v[96:99], v[64:79]
	ds_read_b128 v[248:251], v198 offset:12288
	ds_write_b128 v194, v[140:143]
	v_add_u32_e32 v194, s31, v184
	s_add_i32 s73, s73, 2
	s_cmp_ge_u32 s73, s45
	s_waitcnt vmcnt(2)
	ds_write_b128 v194, v[144:147]
	s_cselect_b64 s[28:29], -1, 0
	ds_write_b128 v185, v[136:139] offset:36864
	s_waitcnt vmcnt(1)
	ds_write_b128 v185, v[132:135] offset:49152
	s_and_b64 vcc, exec, s[28:29]
	s_waitcnt lgkmcnt(5)
	v_mfma_f32_32x32x16_bf16 v[80:95], v[232:235], v[240:243], v[80:95]
	ds_read_b128 v[232:235], v201 offset:24576
	s_waitcnt vmcnt(0)
	ds_write_b128 v186, v[128:131] offset:36864
	v_mfma_f32_32x32x16_bf16 v[64:79], v[236:239], v[240:243], v[64:79]
	ds_read_b128 v[236:239], v181
	ds_read_b128 v[240:243], v187 offset:12288
	s_cbranch_vccnz .Lattn_noloadp
	v_add_co_u32_e32 v128, vcc, 0xfffe0000, v168
	s_nop 1
	v_addc_co_u32_e32 v129, vcc, -1, v169, vcc
	global_load_dwordx4 v[140:143], v[128:129], off
	global_load_dwordx4 v[136:139], v[128:129], off offset:-256
	global_load_dwordx4 v[144:147], v[168:169], off
	global_load_dwordx4 v[132:135], v[168:169], off offset:-256
	s_nop 0
	global_load_dwordx4 v[128:131], v[166:167], off
; __device__ __forceinline__ void finishSM(f32x16& p0, f32x16& p1, float alpha, float& l_reg, bf16x8& pa0, bf16x8& pa1, bf16x8& pa2, bf16x8& pa3) {
; #pragma unroll
;   for (int r = 0; r < 16; ++r) p1[r] = __builtin_amdgcn_exp2f(p1[r]);
;   float ps = 0;
; #pragma unroll
;   for (int r = 0; r < 16; ++r) ps += p0[r];
; #pragma unroll
;   for (int r = 0; r < 16; ++r) ps += p1[r];
;   { auto rr = __builtin_amdgcn_permlane32_swap(__float_as_uint(ps), __float_as_uint(ps), false, false);
;     ps = __uint_as_float(rr[0]) + __uint_as_float(rr[1]); }
;   l_reg = l_reg * alpha + ps;
;     ...
;   PK4(p0, 0, pa0); PK4(p0, 8, pa1); PK4(p1, 0, pa2); PK4(p1, 8, pa3);
;     ...
; }
; __device__ __forceinline__ void qkt(f32x16& p0, f32x16& p1, const char* Ks, const bf16x8* qr, const char* qrl, int r32, int hi) {
;   p0 = f32x16{}; p1 = f32x16{};
; #pragma unroll
;   for (int d0 = 0; d0 < 8; ++d0) { int cb = (d0 * 16 + hi * 8) * 2;
;     bf16x8 b0 = *reinterpret_cast<const bf16x8*>(Ks + KSWZ(r32, cb));
;     bf16x8 b1 = *reinterpret_cast<const bf16x8*>(Ks + KSWZ(32 + r32, cb));
;     p0 = __builtin_amdgcn_mfma_f32_32x32x16_bf16(b0, qr[d0], p0, 0, 0, 0);
;     p1 = __builtin_amdgcn_mfma_f32_32x32x16_bf16(b1, qr[d0], p1, 0, 0, 0); }
; #pragma unroll
;   for (int d0 = 8; d0 < 12; ++d0) { int cb = (d0 * 16 + hi * 8) * 2;
;     bf16x8 b0 = *reinterpret_cast<const bf16x8*>(Ks + KSWZ(r32, cb));
;     bf16x8 b1 = *reinterpret_cast<const bf16x8*>(Ks + KSWZ(32 + r32, cb));
;     bf16x8 qf = *reinterpret_cast<const bf16x8*>(qrl + (((2 * (d0 - 8) + hi) ^ ((r32 >> 1) & 7)) << 4));
;     p0 = __builtin_amdgcn_mfma_f32_32x32x16_bf16(b0, qf, p0, 0, 0, 0);
;     p1 = __builtin_amdgcn_mfma_f32_32x32x16_bf16(b1, qf, p1, 0, 0, 0); }
; }
; __device__ __forceinline__ int v_st(int k, int c) { const int kk = (k & ~0xC) | ((k & 4) << 1) | ((k & 8) >> 1); return ((kk >> 3) * 4 + (c >> 5)) * 512 + ((kk & 7) * 32 + (c & 31)) * 2; }
; __device__ __forceinline__ int v_rd_base(int lane) { return ((lane & 3) << 3) | (((lane >> 2) & 3) << 6) | (((lane >> 4) & 1) << 5) | (((lane >> 5) & 1) << 8); }
; template <int OFF> __device__ __forceinline__ s16x4 tr_read(int vb) {
;   s16x4 r; asm volatile("ds_read_b64_tr_b16 %0, %1 offset:%2" : "=&v"(r) : "v"(vb), "i"(OFF) : "memory"); return r;
; }
; template <int D0> __device__ __forceinline__ void pv_one(f32x16& od, int vb, bf16x8 pa0, bf16x8 pa1, bf16x8 pa2, bf16x8 pa3) {
.Lattn_noloadp:
	s_waitcnt lgkmcnt(1)
	v_mfma_f32_32x32x16_bf16 v[80:95], v[248:251], v[236:239], v[80:95]
	ds_read_b128 v[248:251], v189 offset:24576
	v_cvt_pk_bf16_f32 v158, v158, v159
	v_cvt_pk_bf16_f32 v159, v156, v157
	v_permlane32_swap_b32_e32 v211, v212
	v_cvt_pk_bf16_f32 v156, v162, v163
	v_cvt_pk_bf16_f32 v157, v160, v161
	v_cvt_pk_bf16_f32 v160, v154, v155
	v_mfma_f32_32x32x16_bf16 v[64:79], v[232:235], v[236:239], v[64:79]
	ds_read_b128 v[232:235], v179
	ds_read_b128 v[236:239], v188 offset:12288
	v_cvt_pk_bf16_f32 v161, v152, v153
	v_cvt_pk_bf16_f32 v162, v150, v151
	v_cvt_pk_bf16_f32 v163, v148, v149
	v_add_f32_e32 v211, v211, v212
	v_cvt_pk_bf16_f32 v148, v225, v228
	v_cvt_pk_bf16_f32 v149, v226, v229
	s_waitcnt lgkmcnt(1)
	v_mfma_f32_32x32x16_bf16 v[80:95], v[240:243], v[232:235], v[80:95]
	ds_read_b128 v[240:243], v190 offset:24576
	v_cvt_pk_bf16_f32 v150, v227, v230
	v_cvt_pk_bf16_f32 v151, v223, v224
	v_cvt_pk_bf16_f32 v152, v219, v221
	v_cvt_pk_bf16_f32 v153, v220, v222
	v_cvt_pk_bf16_f32 v154, v215, v217
	v_cvt_pk_bf16_f32 v155, v216, v218
	v_mfma_f32_32x32x16_bf16 v[64:79], v[248:251], v[232:235], v[64:79]
	ds_read_b128 v[248:251], v177
	ds_read_b64_tr_b16 v[232:233], v231 offset:0
	ds_read_b64_tr_b16 v[234:235], v231 offset:2048
	v_fma_f32 v176, v214, v176, v211
	s_waitcnt lgkmcnt(2)
	v_mfma_f32_32x32x16_bf16 v[80:95], v[236:239], v[248:251], v[80:95]
	ds_read_b64_tr_b16 v[236:237], v231 offset:512
	ds_read_b64_tr_b16 v[238:239], v231 offset:2560
	v_mfma_f32_32x32x16_bf16 v[64:79], v[240:243], v[248:251], v[64:79]
	ds_read_b64_tr_b16 v[240:241], v231 offset:1024
	ds_read_b64_tr_b16 v[242:243], v231 offset:3072
	ds_read_b64_tr_b16 v[248:249], v231 offset:1536
	ds_read_b64_tr_b16 v[250:251], v231 offset:3584
	s_waitcnt lgkmcnt(4)
	v_mfma_f32_32x32x16_bf16 v[32:47], v[148:151], v[232:235], v[32:47]
	ds_read_b64_tr_b16 v[232:233], v231 offset:4096
	ds_read_b64_tr_b16 v[234:235], v231 offset:6144
	v_mfma_f32_32x32x16_bf16 v[48:63], v[148:151], v[236:239], v[48:63]
	ds_read_b64_tr_b16 v[236:237], v231 offset:4608
	ds_read_b64_tr_b16 v[238:239], v231 offset:6656
	s_mov_b64 s[100:101], 0x4000
	v_lshl_add_u64 v[166:167], v[166:167], 0, s[100:101]
	v_lshl_add_u64 v[168:169], v[168:169], 0, s[10:11]
	v_max3_f32 v194, v80, v81, v82
	v_max3_f32 v195, v64, v65, v66
	v_max3_f32 v194, v194, v83, v84
	v_max3_f32 v195, v195, v67, v68
	s_waitcnt lgkmcnt(4)
	v_mfma_f32_32x32x16_bf16 v[16:31], v[148:151], v[240:243], v[16:31]
	ds_read_b64_tr_b16 v[240:241], v231 offset:5120
	ds_read_b64_tr_b16 v[242:243], v231 offset:7168
	v_max3_f32 v194, v194, v85, v86
	v_max3_f32 v195, v195, v69, v70
	v_max3_f32 v194, v194, v87, v88
	v_max3_f32 v195, v195, v71, v72
	v_max3_f32 v194, v194, v89, v90
	v_max3_f32 v195, v195, v73, v74
	v_mfma_f32_32x32x16_bf16 v[0:15], v[148:151], v[248:251], v[0:15]
	ds_read_b64_tr_b16 v[248:249], v231 offset:5632
	ds_read_b64_tr_b16 v[250:251], v231 offset:7680
	v_max3_f32 v194, v194, v91, v92
	v_max3_f32 v195, v195, v75, v76
	v_max3_f32 v194, v194, v93, v94
	v_max3_f32 v195, v195, v77, v78
	v_max3_f32 v194, v194, v95, v195
	v_max_f32_e32 v194, v194, v79
	s_waitcnt lgkmcnt(4)
	v_mfma_f32_32x32x16_bf16 v[32:47], v[152:155], v[232:235], v[32:47]
	ds_read_b64_tr_b16 v[232:233], v231 offset:8192
	ds_read_b64_tr_b16 v[234:235], v231 offset:10240
	v_mov_b32_e32 v195, v194
	s_nop 1
	v_permlane32_swap_b32_e32 v194, v195
	v_max_f32_e32 v194, v194, v195
	v_sub_f32_e32 v195, v194, v210
	v_cmp_ge_f32_e32 vcc, s15, v195
	v_mfma_f32_32x32x16_bf16 v[48:63], v[152:155], v[236:239], v[48:63]
	ds_read_b64_tr_b16 v[236:237], v231 offset:8704
	ds_read_b64_tr_b16 v[238:239], v231 offset:10752
	s_cmp_eq_u64 vcc, exec
	s_cselect_b64 s[40:41], -1, 0
	s_cbranch_scc1 .Lattn_fast2p
	v_max_f32_e32 v194, v210, v194
	v_sub_f32_e32 v195, v210, v194
	v_mul_f32_e32 v195, 0x3dd53b94, v195
	v_exp_f32_e32 v213, v195
	v_mov_b32_e32 v210, v194
	s_branch .Lattn_join2p

; __device__ __forceinline__ void partialSM(f32x16& p0, f32x16& p1, float& m_reg, float& mn, float& alpha) {
;     ...
;   for (int r = 0; r < 16; ++r) p0[r] = fmaf(p0[r], C, mnC);
; #pragma unroll
;   for (int r = 0; r < 16; ++r) p1[r] = fmaf(p1[r], C, mnC);
; #pragma unroll
;   for (int r = 0; r < 16; ++r) p0[r] = __builtin_amdgcn_exp2f(p0[r]);
; }
; __device__ __forceinline__ void finishSM(f32x16& p0, f32x16& p1, float alpha, float& l_reg, bf16x8& pa0, bf16x8& pa1, bf16x8& pa2, bf16x8& pa3) {
; #pragma unroll
;   for (int r = 0; r < 16; ++r) p1[r] = __builtin_amdgcn_exp2f(p1[r]);
;   float ps = 0;
; #pragma unroll
;   for (int r = 0; r < 16; ++r) ps += p0[r];
; #pragma unroll
;   for (int r = 0; r < 16; ++r) ps += p1[r];
;   { auto rr = __builtin_amdgcn_permlane32_swap(__float_as_uint(ps), __float_as_uint(ps), false, false);
;     ps = __uint_as_float(rr[0]) + __uint_as_float(rr[1]); }
;   l_reg = l_reg * alpha + ps;
;     ...
;   PK4(p0, 0, pa0); PK4(p0, 8, pa1); PK4(p1, 0, pa2); PK4(p1, 8, pa3);
;     ...
; }
; __device__ __forceinline__ void qkt(f32x16& p0, f32x16& p1, const char* Ks, const bf16x8* qr, const char* qrl, int r32, int hi) {
;   p0 = f32x16{}; p1 = f32x16{};
; #pragma unroll
;   for (int d0 = 0; d0 < 8; ++d0) { int cb = (d0 * 16 + hi * 8) * 2;
;     bf16x8 b0 = *reinterpret_cast<const bf16x8*>(Ks + KSWZ(r32, cb));
;     bf16x8 b1 = *reinterpret_cast<const bf16x8*>(Ks + KSWZ(32 + r32, cb));
;     p0 = __builtin_amdgcn_mfma_f32_32x32x16_bf16(b0, qr[d0], p0, 0, 0, 0);
;     p1 = __builtin_amdgcn_mfma_f32_32x32x16_bf16(b1, qr[d0], p1, 0, 0, 0); }
; #pragma unroll
;   for (int d0 = 8; d0 < 12; ++d0) { int cb = (d0 * 16 + hi * 8) * 2;
;     bf16x8 b0 = *reinterpret_cast<const bf16x8*>(Ks + KSWZ(r32, cb));
;     bf16x8 b1 = *reinterpret_cast<const bf16x8*>(Ks + KSWZ(32 + r32, cb));
;     bf16x8 qf = *reinterpret_cast<const bf16x8*>(qrl + (((2 * (d0 - 8) + hi) ^ ((r32 >> 1) & 7)) << 4));
;     p0 = __builtin_amdgcn_mfma_f32_32x32x16_bf16(b0, qf, p0, 0, 0, 0);
;     p1 = __builtin_amdgcn_mfma_f32_32x32x16_bf16(b1, qf, p1, 0, 0, 0); }
; }
; __device__ __forceinline__ int v_st(int k, int c) { const int kk = (k & ~0xC) | ((k & 4) << 1) | ((k & 8) >> 1); return ((kk >> 3) * 4 + (c >> 5)) * 512 + ((kk & 7) * 32 + (c & 31)) * 2; }
.Lattn_join2p:
	v_mul_f32_e32 v194, 0xbdd53b94, v210
	s_sub_i32 s100, s30, 1
	s_cmp_eq_u32 s30, 0
	s_cselect_b32 s100, 2, s100
	s_add_i32 s101, s30, 1
	s_cmp_lg_u32 s30, 2
	s_cselect_b32 s101, s101, 0
	s_movk_i32 s34, 0x6000
	v_fmamk_f32 v225, v80, 0x3dd53b94, v194
	s_waitcnt lgkmcnt(4)
	v_mfma_f32_32x32x16_bf16 v[16:31], v[152:155], v[240:243], v[16:31]
	ds_read_b64_tr_b16 v[240:241], v231 offset:9216
	ds_read_b64_tr_b16 v[242:243], v231 offset:11264
	v_fmamk_f32 v228, v81, 0x3dd53b94, v194
	v_fmamk_f32 v226, v82, 0x3dd53b94, v194
	v_fmamk_f32 v229, v83, 0x3dd53b94, v194
	v_fmamk_f32 v150, v76, 0x3dd53b94, v194
	v_fmamk_f32 v151, v77, 0x3dd53b94, v194
	v_fmamk_f32 v148, v78, 0x3dd53b94, v194
	v_mfma_f32_32x32x16_bf16 v[0:15], v[152:155], v[248:251], v[0:15]
	ds_read_b64_tr_b16 v[248:249], v231 offset:9728
	ds_read_b64_tr_b16 v[250:251], v231 offset:11776
	v_fmamk_f32 v149, v79, 0x3dd53b94, v194
	v_fmamk_f32 v227, v84, 0x3dd53b94, v194
	v_fmamk_f32 v230, v85, 0x3dd53b94, v194
	v_fmamk_f32 v223, v86, 0x3dd53b94, v194
	v_fmamk_f32 v224, v87, 0x3dd53b94, v194
	v_fmamk_f32 v154, v72, 0x3dd53b94, v194
	s_waitcnt lgkmcnt(4)
	v_mfma_f32_32x32x16_bf16 v[32:47], v[156:159], v[232:235], v[32:47]
	ds_read_b64_tr_b16 v[232:233], v231 offset:12288
	ds_read_b64_tr_b16 v[234:235], v231 offset:14336
	v_fmamk_f32 v155, v73, 0x3dd53b94, v194
	v_fmamk_f32 v152, v74, 0x3dd53b94, v194
	v_fmamk_f32 v153, v75, 0x3dd53b94, v194
	v_fmamk_f32 v219, v88, 0x3dd53b94, v194
	v_fmamk_f32 v221, v89, 0x3dd53b94, v194
	v_fmamk_f32 v220, v90, 0x3dd53b94, v194
	v_mfma_f32_32x32x16_bf16 v[48:63], v[156:159], v[236:239], v[48:63]
	ds_read_b64_tr_b16 v[236:237], v231 offset:12800
	ds_read_b64_tr_b16 v[238:239], v231 offset:14848
	v_fmamk_f32 v222, v91, 0x3dd53b94, v194
	s_waitcnt lgkmcnt(4)
	v_mfma_f32_32x32x16_bf16 v[16:31], v[156:159], v[240:243], v[16:31]
	ds_read_b64_tr_b16 v[240:241], v231 offset:13312
	ds_read_b64_tr_b16 v[242:243], v231 offset:15360
	v_mfma_f32_32x32x16_bf16 v[0:15], v[156:159], v[248:251], v[0:15]
	ds_read_b64_tr_b16 v[248:249], v231 offset:13824
	ds_read_b64_tr_b16 v[250:251], v231 offset:15872
	v_fmamk_f32 v158, v68, 0x3dd53b94, v194
	v_fmamk_f32 v159, v69, 0x3dd53b94, v194
	v_fmamk_f32 v156, v70, 0x3dd53b94, v194
	v_fmamk_f32 v157, v71, 0x3dd53b94, v194
	v_fmamk_f32 v215, v92, 0x3dd53b94, v194
	v_fmamk_f32 v217, v93, 0x3dd53b94, v194
	s_waitcnt lgkmcnt(0)
	s_barrier
	v_mfma_f32_32x32x16_bf16 v[32:47], v[160:163], v[232:235], v[32:47]
	ds_read_b128 v[232:235], v199 offset:36864
	v_fmamk_f32 v216, v94, 0x3dd53b94, v194
	v_fmamk_f32 v218, v95, 0x3dd53b94, v194
	v_mfma_f32_32x32x16_bf16 v[48:63], v[160:163], v[236:239], v[48:63]
	ds_read_b128 v[236:239], v199 offset:49152
	v_mfma_f32_32x32x16_bf16 v[16:31], v[160:163], v[240:243], v[16:31]
	ds_read_b128 v[240:243], v205 offset:36864
	v_mfma_f32_32x32x16_bf16 v[0:15], v[160:163], v[248:251], v[0:15]
	ds_read_b128 v[248:251], v205 offset:49152
	v_fmamk_f32 v162, v64, 0x3dd53b94, v194
	v_fmamk_f32 v163, v65, 0x3dd53b94, v194
	v_fmamk_f32 v160, v66, 0x3dd53b94, v194
	v_fmamk_f32 v161, v67, 0x3dd53b94, v194
	s_and_b64 vcc, exec, s[40:41]
	s_cbranch_vccnz .Lattn_skip_rs2p
	s_and_saveexec_b64 s[18:19], s[38:39]
	ds_write_b32 v175, v213 offset:128
	s_or_b64 exec, exec, s[18:19]
	s_waitcnt lgkmcnt(0)
	v_add_u32_e32 v194, v173, v164
	ds_read_b128 v[64:67], v194 offset:224
	ds_read_b128 v[68:71], v194 offset:192
	ds_read_b128 v[72:75], v194 offset:160
	ds_read_b128 v[76:79], v194 offset:128
	s_waitcnt lgkmcnt(0)
	v_pk_mul_f32 v[44:45], v[44:45], v[64:65]
	v_pk_mul_f32 v[46:47], v[46:47], v[66:67]
	v_pk_mul_f32 v[40:41], v[40:41], v[68:69]
	v_pk_mul_f32 v[42:43], v[42:43], v[70:71]
	v_pk_mul_f32 v[36:37], v[36:37], v[72:73]
	v_pk_mul_f32 v[38:39], v[38:39], v[74:75]
	v_pk_mul_f32 v[32:33], v[32:33], v[76:77]
	v_pk_mul_f32 v[34:35], v[34:35], v[78:79]
	v_pk_mul_f32 v[60:61], v[60:61], v[64:65]
	v_pk_mul_f32 v[62:63], v[62:63], v[66:67]
	v_pk_mul_f32 v[56:57], v[56:57], v[68:69]
	v_pk_mul_f32 v[58:59], v[58:59], v[70:71]
	v_pk_mul_f32 v[52:53], v[52:53], v[72:73]
	v_pk_mul_f32 v[54:55], v[54:55], v[74:75]
	v_pk_mul_f32 v[48:49], v[48:49], v[76:77]
	v_pk_mul_f32 v[50:51], v[50:51], v[78:79]
	v_pk_mul_f32 v[28:29], v[28:29], v[64:65]
	v_pk_mul_f32 v[30:31], v[30:31], v[66:67]
	v_pk_mul_f32 v[24:25], v[24:25], v[68:69]
	v_pk_mul_f32 v[26:27], v[26:27], v[70:71]
	v_pk_mul_f32 v[20:21], v[20:21], v[72:73]
	v_pk_mul_f32 v[22:23], v[22:23], v[74:75]
	v_pk_mul_f32 v[16:17], v[16:17], v[76:77]
	v_pk_mul_f32 v[18:19], v[18:19], v[78:79]
	v_pk_mul_f32 v[12:13], v[12:13], v[64:65]
	v_pk_mul_f32 v[14:15], v[14:15], v[66:67]
	v_pk_mul_f32 v[8:9], v[8:9], v[68:69]
	v_pk_mul_f32 v[10:11], v[10:11], v[70:71]
	v_pk_mul_f32 v[4:5], v[4:5], v[72:73]
	v_pk_mul_f32 v[6:7], v[6:7], v[74:75]
	v_pk_mul_f32 v[0:1], v[0:1], v[76:77]
	v_pk_mul_f32 v[2:3], v[2:3], v[78:79]

; __device__ __forceinline__ void finishSM(f32x16& p0, f32x16& p1, float alpha, float& l_reg, bf16x8& pa0, bf16x8& pa1, bf16x8& pa2, bf16x8& pa3) {
; #pragma unroll
;   for (int r = 0; r < 16; ++r) p1[r] = __builtin_amdgcn_exp2f(p1[r]);
;   float ps = 0;
; #pragma unroll
;   for (int r = 0; r < 16; ++r) ps += p0[r];
; #pragma unroll
;   for (int r = 0; r < 16; ++r) ps += p1[r];
;   { auto rr = __builtin_amdgcn_permlane32_swap(__float_as_uint(ps), __float_as_uint(ps), false, false);
;     ps = __uint_as_float(rr[0]) + __uint_as_float(rr[1]); }
;   l_reg = l_reg * alpha + ps;
;     ...
;   PK4(p0, 0, pa0); PK4(p0, 8, pa1); PK4(p1, 0, pa2); PK4(p1, 8, pa3);
;     ...
; }
; __device__ __forceinline__ void qkt(f32x16& p0, f32x16& p1, const char* Ks, const bf16x8* qr, const char* qrl, int r32, int hi) {
;   p0 = f32x16{}; p1 = f32x16{};
; #pragma unroll
;   for (int d0 = 0; d0 < 8; ++d0) { int cb = (d0 * 16 + hi * 8) * 2;
;     bf16x8 b0 = *reinterpret_cast<const bf16x8*>(Ks + KSWZ(r32, cb));
;     bf16x8 b1 = *reinterpret_cast<const bf16x8*>(Ks + KSWZ(32 + r32, cb));
;     p0 = __builtin_amdgcn_mfma_f32_32x32x16_bf16(b0, qr[d0], p0, 0, 0, 0);
;     p1 = __builtin_amdgcn_mfma_f32_32x32x16_bf16(b1, qr[d0], p1, 0, 0, 0); }
; #pragma unroll
;   for (int d0 = 8; d0 < 12; ++d0) { int cb = (d0 * 16 + hi * 8) * 2;
;     bf16x8 b0 = *reinterpret_cast<const bf16x8*>(Ks + KSWZ(r32, cb));
;     bf16x8 b1 = *reinterpret_cast<const bf16x8*>(Ks + KSWZ(32 + r32, cb));
;     bf16x8 qf = *reinterpret_cast<const bf16x8*>(qrl + (((2 * (d0 - 8) + hi) ^ ((r32 >> 1) & 7)) << 4));
;     p0 = __builtin_amdgcn_mfma_f32_32x32x16_bf16(b0, qf, p0, 0, 0, 0);
;     p1 = __builtin_amdgcn_mfma_f32_32x32x16_bf16(b1, qf, p1, 0, 0, 0); }
; }
.Lattn_steady:
	s_lshl_b32 s31, s30, 14
	v_add_u32_e32 v180, s31, v178
	v_exp_f32_e32 v225, v225
	v_exp_f32_e32 v228, v228
	v_exp_f32_e32 v226, v226
	v_add_f32_e32 v211, v225, v228
	s_waitcnt lgkmcnt(2)
	v_mfma_f32_32x32x16_bf16 v[80:95], v[232:235], v[124:127], 0
	ds_read_b128 v[232:235], v206 offset:36864
	v_exp_f32_e32 v229, v229
	v_add_f32_e32 v211, v226, v211
	v_exp_f32_e32 v227, v227
	v_add_f32_e32 v211, v229, v211
	v_mfma_f32_32x32x16_bf16 v[64:79], v[236:239], v[124:127], 0
	ds_read_b128 v[236:239], v206 offset:49152
	v_exp_f32_e32 v230, v230
	v_add_f32_e32 v211, v227, v211
	v_exp_f32_e32 v223, v223
	v_add_f32_e32 v211, v230, v211
	s_waitcnt lgkmcnt(2)
	v_mfma_f32_32x32x16_bf16 v[80:95], v[240:243], v[120:123], v[80:95]
	ds_read_b128 v[240:243], v208 offset:36864
	v_exp_f32_e32 v224, v224
	v_add_f32_e32 v211, v223, v211
	v_exp_f32_e32 v219, v219
	v_add_f32_e32 v211, v224, v211
	v_mfma_f32_32x32x16_bf16 v[64:79], v[248:251], v[120:123], v[64:79]
	ds_read_b128 v[248:251], v208 offset:49152
	v_exp_f32_e32 v221, v221
	v_add_f32_e32 v211, v219, v211
	v_exp_f32_e32 v220, v220
	v_add_f32_e32 v211, v221, v211
	s_waitcnt lgkmcnt(2)
	v_mfma_f32_32x32x16_bf16 v[80:95], v[232:235], v[116:119], v[80:95]
	ds_read_b128 v[232:235], v207 offset:36864
	v_exp_f32_e32 v222, v222
	v_add_f32_e32 v211, v220, v211
	v_exp_f32_e32 v215, v215
	v_add_f32_e32 v211, v222, v211
	v_mfma_f32_32x32x16_bf16 v[64:79], v[236:239], v[116:119], v[64:79]
	ds_read_b128 v[236:239], v207 offset:49152
	v_exp_f32_e32 v217, v217
	v_add_f32_e32 v211, v215, v211
	v_exp_f32_e32 v216, v216
	v_add_f32_e32 v211, v217, v211
	s_waitcnt lgkmcnt(2)
	v_mfma_f32_32x32x16_bf16 v[80:95], v[240:243], v[112:115], v[80:95]
	ds_read_b128 v[240:243], v204 offset:36864
	v_exp_f32_e32 v218, v218
	v_add_f32_e32 v211, v216, v211
	v_exp_f32_e32 v162, v162
	v_add_f32_e32 v211, v218, v211
	v_mfma_f32_32x32x16_bf16 v[64:79], v[248:251], v[112:115], v[64:79]
	ds_read_b128 v[248:251], v204 offset:49152
	v_exp_f32_e32 v163, v163
	v_exp_f32_e32 v160, v160
	v_exp_f32_e32 v161, v161
	s_waitcnt lgkmcnt(2)
	v_mfma_f32_32x32x16_bf16 v[80:95], v[232:235], v[108:111], v[80:95]
	ds_read_b128 v[232:235], v203 offset:36864
	v_exp_f32_e32 v158, v158
	v_exp_f32_e32 v159, v159
	v_exp_f32_e32 v156, v156
	v_mfma_f32_32x32x16_bf16 v[64:79], v[236:239], v[108:111], v[64:79]
	ds_read_b128 v[236:239], v203 offset:49152
	v_exp_f32_e32 v157, v157
	v_exp_f32_e32 v154, v154
	v_exp_f32_e32 v155, v155
	s_waitcnt lgkmcnt(2)
	v_mfma_f32_32x32x16_bf16 v[80:95], v[240:243], v[104:107], v[80:95]
	ds_read_b128 v[240:243], v200 offset:36864
	v_exp_f32_e32 v152, v152
	v_exp_f32_e32 v153, v153
	v_exp_f32_e32 v150, v150
	v_mfma_f32_32x32x16_bf16 v[64:79], v[248:251], v[104:107], v[64:79]
	ds_read_b128 v[248:251], v200 offset:49152
	v_exp_f32_e32 v151, v151
	v_exp_f32_e32 v148, v148
	v_exp_f32_e32 v149, v149
	s_waitcnt lgkmcnt(2)
	v_mfma_f32_32x32x16_bf16 v[80:95], v[232:235], v[100:103], v[80:95]
	ds_read_b128 v[232:235], v191 offset:36864
	v_add_f32_e32 v212, v162, v163
	v_add_f32_e32 v212, v160, v212
	v_add_f32_e32 v212, v161, v212
	v_add_f32_e32 v212, v158, v212
	v_add_f32_e32 v212, v159, v212
	v_add_f32_e32 v212, v156, v212
	v_mfma_f32_32x32x16_bf16 v[64:79], v[236:239], v[100:103], v[64:79]
	ds_read_b128 v[236:239], v202 offset:49152
	v_add_f32_e32 v212, v157, v212
	v_add_f32_e32 v212, v154, v212
	v_add_f32_e32 v212, v155, v212
	v_add_f32_e32 v212, v152, v212
	v_add_f32_e32 v212, v153, v212
	v_add_f32_e32 v212, v150, v212
	s_waitcnt lgkmcnt(2)
	v_mfma_f32_32x32x16_bf16 v[80:95], v[240:243], v[96:99], v[80:95]
	ds_read_b128 v[240:243], v182
	v_add_f32_e32 v212, v151, v212
	v_add_f32_e32 v212, v148, v212
	v_add_f32_e32 v212, v149, v212
	v_add_f32_e32 v211, v211, v212
	v_mov_b32_e32 v212, v211
	s_lshl_b32 s19, s18, 14
	v_add_u32_e32 v231, s19, v183
	s_waitcnt vmcnt(0)
	v_mfma_f32_32x32x16_bf16 v[64:79], v[248:251], v[96:99], v[64:79]
	ds_read_b128 v[248:251], v198 offset:36864
	ds_write_b128 v231, v[140:143]
	v_add_u32_e32 v140, s19, v184
	ds_write_b128 v140, v[144:147]
	ds_write_b128 v185, v[136:139] offset:12288
	ds_write_b128 v185, v[132:135] offset:24576
	s_mov_b32 s18, 0xfffa0000
	ds_write_b128 v186, v[128:131] offset:12288
	v_add_co_u32_e32 v128, vcc, s18, v168
	s_mov_b32 s18, 0xfffc0000
	s_nop 0
	s_waitcnt lgkmcnt(6)
; __device__ __forceinline__ void partialSM(f32x16& p0, f32x16& p1, float& m_reg, float& mn, float& alpha) {
;     ...
;   for (int r = 1; r < 16; ++r) pmax = fmaxf(pmax, p0[r]);
; #pragma unroll
;   for (int r = 0; r < 16; ++r) pmax = fmaxf(pmax, p1[r]);
;   { auto rr = __builtin_amdgcn_permlane32_swap(__float_as_uint(pmax), __float_as_uint(pmax), false, false);
;     pmax = fmaxf(__uint_as_float(rr[0]), __uint_as_float(rr[1])); }
;   if (__builtin_expect(__all(pmax - m_reg <= THR / SCALE), 1)) { mn = m_reg; alpha = 1.f; }
;   else { mn = fmaxf(m_reg, pmax); alpha = __builtin_amdgcn_exp2f((m_reg - mn) * C); m_reg = mn; }
;   float mnC = -mn * C;
; #pragma unroll
;   for (int r = 0; r < 16; ++r) p0[r] = fmaf(p0[r], C, mnC);
; #pragma unroll
;   for (int r = 0; r < 16; ++r) p1[r] = fmaf(p1[r], C, mnC);
; #pragma unroll
;   for (int r = 0; r < 16; ++r) p0[r] = __builtin_amdgcn_exp2f(p0[r]);
; }
; __device__ __forceinline__ void finishSM(f32x16& p0, f32x16& p1, float alpha, float& l_reg, bf16x8& pa0, bf16x8& pa1, bf16x8& pa2, bf16x8& pa3) {
; #pragma unroll
;   for (int r = 0; r < 16; ++r) p1[r] = __builtin_amdgcn_exp2f(p1[r]);
;   float ps = 0;
; #pragma unroll
;   for (int r = 0; r < 16; ++r) ps += p0[r];
; #pragma unroll
;   for (int r = 0; r < 16; ++r) ps += p1[r];
;   { auto rr = __builtin_amdgcn_permlane32_swap(__float_as_uint(ps), __float_as_uint(ps), false, false);
;     ps = __uint_as_float(rr[0]) + __uint_as_float(rr[1]); }
;   l_reg = l_reg * alpha + ps;
;     ...
;   PK4(p0, 0, pa0); PK4(p0, 8, pa1); PK4(p1, 0, pa2); PK4(p1, 8, pa3);
;     ...
; }
; __device__ __forceinline__ void qkt(f32x16& p0, f32x16& p1, const char* Ks, const bf16x8* qr, const char* qrl, int r32, int hi) {
;   p0 = f32x16{}; p1 = f32x16{};
; #pragma unroll
;   for (int d0 = 0; d0 < 8; ++d0) { int cb = (d0 * 16 + hi * 8) * 2;
;     bf16x8 b0 = *reinterpret_cast<const bf16x8*>(Ks + KSWZ(r32, cb));
;     bf16x8 b1 = *reinterpret_cast<const bf16x8*>(Ks + KSWZ(32 + r32, cb));
;     p0 = __builtin_amdgcn_mfma_f32_32x32x16_bf16(b0, qr[d0], p0, 0, 0, 0);
;     p1 = __builtin_amdgcn_mfma_f32_32x32x16_bf16(b1, qr[d0], p1, 0, 0, 0); }
; #pragma unroll
;   for (int d0 = 8; d0 < 12; ++d0) { int cb = (d0 * 16 + hi * 8) * 2;
;     bf16x8 b0 = *reinterpret_cast<const bf16x8*>(Ks + KSWZ(r32, cb));
;     bf16x8 b1 = *reinterpret_cast<const bf16x8*>(Ks + KSWZ(32 + r32, cb));
	v_mfma_f32_32x32x16_bf16 v[80:95], v[232:235], v[240:243], v[80:95]
	ds_read_b128 v[232:235], v201 offset:49152
	v_addc_co_u32_e32 v129, vcc, -1, v169, vcc
	v_add_co_u32_e32 v130, vcc, s18, v168
	s_movk_i32 s18, 0xe000
	s_nop 0
	v_addc_co_u32_e32 v131, vcc, -1, v169, vcc
	global_load_dwordx4 v[140:143], v[128:129], off
	global_load_dwordx4 v[136:139], v[128:129], off offset:-256
	global_load_dwordx4 v[144:147], v[130:131], off
	v_mfma_f32_32x32x16_bf16 v[64:79], v[236:239], v[240:243], v[64:79]
	ds_read_b128 v[236:239], v181
	ds_read_b128 v[240:243], v187 offset:36864
	global_load_dwordx4 v[132:135], v[130:131], off offset:-256
	v_add_co_u32_e32 v128, vcc, s18, v166
	s_nop 1
	v_addc_co_u32_e32 v129, vcc, -1, v167, vcc
	global_load_dwordx4 v[128:131], v[128:129], off
	v_cvt_pk_bf16_f32 v158, v158, v159
	v_cvt_pk_bf16_f32 v159, v156, v157
	s_waitcnt lgkmcnt(1)
	v_mfma_f32_32x32x16_bf16 v[80:95], v[248:251], v[236:239], v[80:95]
	ds_read_b128 v[248:251], v189 offset:49152
	v_permlane32_swap_b32_e32 v211, v212
	v_cvt_pk_bf16_f32 v156, v162, v163
	v_cvt_pk_bf16_f32 v157, v160, v161
	v_cvt_pk_bf16_f32 v160, v154, v155
	v_cvt_pk_bf16_f32 v161, v152, v153
	v_cvt_pk_bf16_f32 v162, v150, v151
	v_mfma_f32_32x32x16_bf16 v[64:79], v[232:235], v[236:239], v[64:79]
	ds_read_b128 v[232:235], v179
	ds_read_b128 v[236:239], v188 offset:36864
	v_cvt_pk_bf16_f32 v163, v148, v149
	v_add_f32_e32 v211, v211, v212
	v_cvt_pk_bf16_f32 v148, v225, v228
	v_cvt_pk_bf16_f32 v149, v226, v229
	v_cvt_pk_bf16_f32 v150, v227, v230
	v_cvt_pk_bf16_f32 v151, v223, v224
	s_waitcnt lgkmcnt(1)
	v_mfma_f32_32x32x16_bf16 v[80:95], v[240:243], v[232:235], v[80:95]
	ds_read_b128 v[240:243], v190 offset:49152
	v_cvt_pk_bf16_f32 v152, v219, v221
	v_cvt_pk_bf16_f32 v153, v220, v222
	v_cvt_pk_bf16_f32 v154, v215, v217
	v_cvt_pk_bf16_f32 v155, v216, v218
	v_fma_f32 v176, v209, v176, v211
	v_mfma_f32_32x32x16_bf16 v[64:79], v[248:251], v[232:235], v[64:79]
	ds_read_b128 v[248:251], v177
	ds_read_b64_tr_b16 v[232:233], v180 offset:0
	ds_read_b64_tr_b16 v[234:235], v180 offset:2048
	s_waitcnt lgkmcnt(2)
	v_mfma_f32_32x32x16_bf16 v[80:95], v[236:239], v[248:251], v[80:95]
	ds_read_b64_tr_b16 v[236:237], v180 offset:512
	ds_read_b64_tr_b16 v[238:239], v180 offset:2560
	v_mfma_f32_32x32x16_bf16 v[64:79], v[240:243], v[248:251], v[64:79]
	ds_read_b64_tr_b16 v[240:241], v180 offset:1024
	ds_read_b64_tr_b16 v[242:243], v180 offset:3072
	ds_read_b64_tr_b16 v[248:249], v180 offset:1536
	ds_read_b64_tr_b16 v[250:251], v180 offset:3584
	s_waitcnt lgkmcnt(4)
	v_mfma_f32_32x32x16_bf16 v[32:47], v[148:151], v[232:235], v[32:47]
	ds_read_b64_tr_b16 v[232:233], v180 offset:4096
	ds_read_b64_tr_b16 v[234:235], v180 offset:6144
	v_mfma_f32_32x32x16_bf16 v[48:63], v[148:151], v[236:239], v[48:63]
	ds_read_b64_tr_b16 v[236:237], v180 offset:4608
	ds_read_b64_tr_b16 v[238:239], v180 offset:6656
	v_max3_f32 v194, v80, v81, v82
	v_max3_f32 v195, v64, v65, v66
	v_max3_f32 v194, v194, v83, v84
	v_max3_f32 v195, v195, v67, v68
	v_max3_f32 v194, v194, v85, v86
	v_max3_f32 v195, v195, v69, v70
	s_waitcnt lgkmcnt(4)
	v_mfma_f32_32x32x16_bf16 v[16:31], v[148:151], v[240:243], v[16:31]
	ds_read_b64_tr_b16 v[240:241], v180 offset:5120
	ds_read_b64_tr_b16 v[242:243], v180 offset:7168
	v_max3_f32 v194, v194, v87, v88
	v_max3_f32 v195, v195, v71, v72
	v_max3_f32 v194, v194, v89, v90
	v_max3_f32 v195, v195, v73, v74
	v_max3_f32 v194, v194, v91, v92
	v_max3_f32 v195, v195, v75, v76
	v_mfma_f32_32x32x16_bf16 v[0:15], v[148:151], v[248:251], v[0:15]
	ds_read_b64_tr_b16 v[248:249], v180 offset:5632
	ds_read_b64_tr_b16 v[250:251], v180 offset:7680
	v_max3_f32 v194, v194, v93, v94
	v_max3_f32 v195, v195, v77, v78
	v_max3_f32 v194, v194, v95, v195
	v_max_f32_e32 v194, v194, v79
	v_mov_b32_e32 v195, v194
	s_nop 1
	s_waitcnt lgkmcnt(4)
	v_mfma_f32_32x32x16_bf16 v[32:47], v[152:155], v[232:235], v[32:47]
	ds_read_b64_tr_b16 v[232:233], v180 offset:8192
	ds_read_b64_tr_b16 v[234:235], v180 offset:10240
	v_permlane32_swap_b32_e32 v194, v195
	v_max_f32_e32 v194, v194, v195
	v_sub_f32_e32 v195, v194, v210
	v_cmp_ge_f32_e32 vcc, s15, v195
	v_mfma_f32_32x32x16_bf16 v[48:63], v[152:155], v[236:239], v[48:63]
	ds_read_b64_tr_b16 v[236:237], v180 offset:8704
	ds_read_b64_tr_b16 v[238:239], v180 offset:10752
	s_cmp_eq_u64 vcc, exec
	s_cselect_b64 s[40:41], -1, 0
	s_cbranch_scc1 .Lattn_fast1
	v_max_f32_e32 v194, v210, v194
	v_sub_f32_e32 v195, v210, v194
	v_mul_f32_e32 v195, 0x3dd53b94, v195
	v_exp_f32_e32 v214, v195
	v_mov_b32_e32 v210, v194
	s_branch .Lattn_join1
